# K-loop LDS read bases: second-k-tile reads use the resident first-k-tile base register with a larger immediate offset; 2-4 VALU adds per iteration removed from the head of the load segments
# speedup vs baseline: 1.0082x; 1.0082x over previous
.LBB0_164:
	s_and_b32 s3, s13, 3
	s_add_i32 m0, s59, 0x18000
	v_lshl_add_u64 v[8:9], v[8:9], 0, s[90:91]
	s_add_i32 s65, s16, -1
	s_lshl_b32 s25, s24, 13
	s_lshl_b32 s28, s3, 5
	s_lshl_b32 s3, s3, 12
	s_waitcnt vmcnt(2)
	s_barrier
	global_load_lds_dwordx4 v[8:9], off
	v_lshl_add_u64 v[6:7], v[6:7], 0, s[90:91]
	s_add_i32 m0, s59, 0x1a000
	s_add_i32 s66, s59, 0x8000
	s_add_i32 s67, s59, 0xa000
	global_load_lds_dwordx4 v[6:7], off
	v_lshl_add_u64 v[2:3], v[2:3], 0, s[90:91]
	s_mov_b32 m0, s66
	s_add_u32 s26, s10, 0x40080
	global_load_lds_dwordx4 v[2:3], off
	v_lshl_add_u64 v[2:3], v[4:5], 0, s[90:91]
	s_mov_b32 m0, s67
	s_addc_u32 s27, s11, 0
	global_load_lds_dwordx4 v[2:3], off
	s_add_i32 m0, s59, 0x1c000
	v_lshl_add_u64 v[2:3], s[26:27], 0, v[154:155]
	global_load_lds_dwordx4 v[2:3], off
	v_lshl_add_u64 v[2:3], s[26:27], 0, v[158:159]
	s_add_i32 m0, s59, 0x1e000
	v_bfe_u32 v4, v0, 4, 2
	global_load_lds_dwordx4 v[2:3], off
	v_and_b32_e32 v3, 15, v0
	v_lshlrev_b32_e32 v2, 3, v4
	v_lshlrev_b32_e32 v4, 4, v4
	v_lshlrev_b32_e32 v0, 2, v0
	v_lshl_or_b32 v147, s24, 6, v3
	v_lshl_or_b32 v3, v3, 6, v4
	v_and_b32_e32 v0, 32, v0
	s_cmpk_lt_u32 s12, 0x100
	v_bitop3_b32 v197, v3, s3, v0 bitop3:0xde
	v_add_u32_e32 v244, 0x10000, v197
	s_cselect_b64 s[46:47], -1, 0
	s_bfe_u32 s68, s13, 0x10001
	s_lshl_b32 s3, s13, 6
	v_readlane_b32 s12, v254, 14
	v_bitop3_b32 v5, v3, s25, v0 bitop3:0xde
	v_and_or_b32 v0, s3, 64, v4
	v_readlane_b32 s13, v254, 15
	v_and_b32_e32 v3, 1, v10
	s_waitcnt vmcnt(6)
	v_or_b32_e32 v198, s28, v2
	v_lshl_add_u64 v[162:163], s[12:13], 0, v[0:1]
	v_readlane_b32 s12, v254, 18
	v_readlane_b32 s13, v254, 19
	v_or_b32_e32 v199, 0x9000000, v198
	v_and_or_b32 v160, s28, 32, v2
	v_lshl_add_u64 v[164:165], s[12:13], 0, v[0:1]
	v_lshlrev_b32_e32 v0, 14, v10
	v_and_b32_e32 v0, 0xffff8000, v0
	v_lshl_add_u32 v0, v11, 11, v0
	v_lshl_or_b32 v0, v3, 6, v0
	v_lshl_add_u32 v166, v12, 1, v0
	v_lshlrev_b32_e32 v0, 14, v13
	v_and_b32_e32 v0, 0xffff8000, v0
	v_lshl_add_u32 v0, v14, 11, v0
	v_and_b32_e32 v3, 1, v13
	v_lshl_or_b32 v0, v3, 6, v0
	s_ashr_i32 s69, s14, 31
	s_ashr_i32 s70, s15, 31
	v_mov_b32_e32 v167, v1
	v_lshl_add_u32 v168, v15, 1, v0
	v_mov_b32_e32 v169, v1
	s_mov_b32 s71, 0
	v_add_u32_e32 v200, 0, v5
	s_lshl_b32 s72, s28, 2
	v_lshlrev_b32_e32 v201, 2, v2
	s_barrier
	s_branch .LBB0_167

.Lk1_body:
	ds_read_b128 v[130:133], v244
	ds_read_b128 v[134:137], v244 offset:1024
	ds_read_b128 v[138:141], v244 offset:2048
	ds_read_b128 v[142:145], v244 offset:3072
	ds_read_b128 v[170:173], v244 offset:16384
	ds_read_b128 v[174:177], v244 offset:17408
	ds_read_b128 v[202:205], v244 offset:18432
	ds_read_b128 v[206:209], v244 offset:19456
	s_add_i32 m0, s59, 0xc000
	ds_read_b128 v[210:213], v200
	ds_read_b128 v[216:219], v200 offset:1024
	ds_read_b128 v[220:223], v200 offset:2048
	ds_read_b128 v[224:227], v200 offset:3072
	ds_read_b128 v[228:231], v200 offset:4096
	ds_read_b128 v[232:235], v200 offset:5120
	ds_read_b128 v[236:239], v200 offset:6144
	ds_read_b128 v[240:243], v200 offset:7168
	global_load_lds_dwordx4 v166, s[8:9]
	s_add_i32 m0, s59, 0xe000
	s_nop 0
	global_load_lds_dwordx4 v168, s[8:9]
	s_waitcnt vmcnt(8)
	s_waitcnt lgkmcnt(0)
	s_barrier
	s_waitcnt lgkmcnt(0)
	v_mfma_f32_16x16x32_bf16 v[126:129], v[130:133], v[210:213], v[126:129]
	v_mfma_f32_16x16x32_bf16 v[122:125], v[138:141], v[210:213], v[122:125]
	v_mfma_f32_16x16x32_bf16 v[110:113], v[130:133], v[220:223], v[110:113]
	v_mfma_f32_16x16x32_bf16 v[106:109], v[138:141], v[220:223], v[106:109]
	v_mfma_f32_16x16x32_bf16 v[94:97], v[130:133], v[228:231], v[94:97]
	v_mfma_f32_16x16x32_bf16 v[90:93], v[138:141], v[228:231], v[90:93]
	v_mfma_f32_16x16x32_bf16 v[78:81], v[130:133], v[236:239], v[78:81]
	v_mfma_f32_16x16x32_bf16 v[74:77], v[138:141], v[236:239], v[74:77]
	v_mfma_f32_16x16x32_bf16 v[126:129], v[134:137], v[216:219], v[126:129]
	v_mfma_f32_16x16x32_bf16 v[122:125], v[142:145], v[216:219], v[122:125]
	v_mfma_f32_16x16x32_bf16 v[110:113], v[134:137], v[224:227], v[110:113]
	v_mfma_f32_16x16x32_bf16 v[106:109], v[142:145], v[224:227], v[106:109]
	v_mfma_f32_16x16x32_bf16 v[94:97], v[134:137], v[232:235], v[94:97]
	v_mfma_f32_16x16x32_bf16 v[90:93], v[142:145], v[232:235], v[90:93]
	v_mfma_f32_16x16x32_bf16 v[78:81], v[134:137], v[240:243], v[78:81]
	v_mfma_f32_16x16x32_bf16 v[74:77], v[142:145], v[240:243], v[74:77]
	v_mfma_f32_16x16x32_bf16 v[118:121], v[170:173], v[210:213], v[118:121]
	v_mfma_f32_16x16x32_bf16 v[114:117], v[202:205], v[210:213], v[114:117]
	v_mfma_f32_16x16x32_bf16 v[102:105], v[170:173], v[220:223], v[102:105]
	v_mfma_f32_16x16x32_bf16 v[98:101], v[202:205], v[220:223], v[98:101]
	v_mfma_f32_16x16x32_bf16 v[86:89], v[170:173], v[228:231], v[86:89]
	v_mfma_f32_16x16x32_bf16 v[82:85], v[202:205], v[228:231], v[82:85]
	v_mfma_f32_16x16x32_bf16 v[70:73], v[170:173], v[236:239], v[70:73]
	v_mfma_f32_16x16x32_bf16 v[66:69], v[202:205], v[236:239], v[66:69]
	v_mfma_f32_16x16x32_bf16 v[118:121], v[174:177], v[216:219], v[118:121]
	v_mfma_f32_16x16x32_bf16 v[114:117], v[206:209], v[216:219], v[114:117]
	v_mfma_f32_16x16x32_bf16 v[102:105], v[174:177], v[224:227], v[102:105]
	v_mfma_f32_16x16x32_bf16 v[98:101], v[206:209], v[224:227], v[98:101]
	v_mfma_f32_16x16x32_bf16 v[86:89], v[174:177], v[232:235], v[86:89]
	v_mfma_f32_16x16x32_bf16 v[82:85], v[206:209], v[232:235], v[82:85]
	v_mfma_f32_16x16x32_bf16 v[70:73], v[174:177], v[240:243], v[70:73]
	v_mfma_f32_16x16x32_bf16 v[66:69], v[206:209], v[240:243], v[66:69]
	s_barrier
	s_add_i32 s30, s30, s61
	s_mov_b32 m0, s30
	ds_read_b128 v[210:213], v200 offset:16384
	ds_read_b128 v[216:219], v200 offset:17408
	ds_read_b128 v[220:223], v200 offset:18432
	ds_read_b128 v[224:227], v200 offset:19456
	ds_read_b128 v[228:231], v200 offset:20480
	ds_read_b128 v[232:235], v200 offset:21504
	ds_read_b128 v[236:239], v200 offset:22528
	ds_read_b128 v[240:243], v200 offset:23552
	global_load_lds_dwordx4 v154, s[10:11]
	s_add_i32 m0, s30, 0x2000
	s_add_u32 s42, s10, 0x40000
	s_addc_u32 s43, s11, 0
	s_add_i32 s30, s31, s61
	global_load_lds_dwordx4 v158, s[10:11]
	s_mov_b32 m0, s30
	s_nop 0
	global_load_lds_dwordx4 v154, s[42:43]
	s_mov_b32 m0, s59
	s_nop 0
	global_load_lds_dwordx4 v152, s[12:13]
	s_mov_b32 m0, s62
	s_nop 0
	global_load_lds_dwordx4 v156, s[12:13]
	s_waitcnt vmcnt(7)
	s_waitcnt lgkmcnt(0)
	s_barrier
	s_waitcnt lgkmcnt(0)
	v_mfma_f32_16x16x32_bf16 v[62:65], v[130:133], v[210:213], v[62:65]
	v_mfma_f32_16x16x32_bf16 v[58:61], v[138:141], v[210:213], v[58:61]
	v_mfma_f32_16x16x32_bf16 v[46:49], v[130:133], v[220:223], v[46:49]
	v_mfma_f32_16x16x32_bf16 v[42:45], v[138:141], v[220:223], v[42:45]
	v_mfma_f32_16x16x32_bf16 v[30:33], v[130:133], v[228:231], v[30:33]
	v_mfma_f32_16x16x32_bf16 v[26:29], v[138:141], v[228:231], v[26:29]
	v_mfma_f32_16x16x32_bf16 v[14:17], v[130:133], v[236:239], v[14:17]
	v_mfma_f32_16x16x32_bf16 v[10:13], v[138:141], v[236:239], v[10:13]
	v_mfma_f32_16x16x32_bf16 v[62:65], v[134:137], v[216:219], v[62:65]
	v_mfma_f32_16x16x32_bf16 v[58:61], v[142:145], v[216:219], v[58:61]
	v_mfma_f32_16x16x32_bf16 v[46:49], v[134:137], v[224:227], v[46:49]
	v_mfma_f32_16x16x32_bf16 v[42:45], v[142:145], v[224:227], v[42:45]
	v_mfma_f32_16x16x32_bf16 v[30:33], v[134:137], v[232:235], v[30:33]
	v_mfma_f32_16x16x32_bf16 v[26:29], v[142:145], v[232:235], v[26:29]
	v_mfma_f32_16x16x32_bf16 v[14:17], v[134:137], v[240:243], v[14:17]
	v_mfma_f32_16x16x32_bf16 v[10:13], v[142:145], v[240:243], v[10:13]
	v_mfma_f32_16x16x32_bf16 v[54:57], v[170:173], v[210:213], v[54:57]
	v_mfma_f32_16x16x32_bf16 v[50:53], v[202:205], v[210:213], v[50:53]
	v_mfma_f32_16x16x32_bf16 v[38:41], v[170:173], v[220:223], v[38:41]
	v_mfma_f32_16x16x32_bf16 v[34:37], v[202:205], v[220:223], v[34:37]
	v_mfma_f32_16x16x32_bf16 v[22:25], v[170:173], v[228:231], v[22:25]
	v_mfma_f32_16x16x32_bf16 v[18:21], v[202:205], v[228:231], v[18:21]
	v_mfma_f32_16x16x32_bf16 v[6:9], v[170:173], v[236:239], v[6:9]
	v_mfma_f32_16x16x32_bf16 v[2:5], v[202:205], v[236:239], v[2:5]
	v_mfma_f32_16x16x32_bf16 v[54:57], v[174:177], v[216:219], v[54:57]
	v_mfma_f32_16x16x32_bf16 v[50:53], v[206:209], v[216:219], v[50:53]
	v_mfma_f32_16x16x32_bf16 v[38:41], v[174:177], v[224:227], v[38:41]
	v_mfma_f32_16x16x32_bf16 v[34:37], v[206:209], v[224:227], v[34:37]
	v_mfma_f32_16x16x32_bf16 v[22:25], v[174:177], v[232:235], v[22:25]
	v_mfma_f32_16x16x32_bf16 v[18:21], v[206:209], v[232:235], v[18:21]
	v_mfma_f32_16x16x32_bf16 v[6:9], v[174:177], v[240:243], v[6:9]
	v_mfma_f32_16x16x32_bf16 v[2:5], v[206:209], v[240:243], v[2:5]
	s_barrier
	s_add_i32 m0, s30, 0x2000
	s_nop 0
	global_load_lds_dwordx4 v158, s[42:43]
	s_add_i32 s30, 0, 0x18000
	s_add_i32 s31, 0, 0x1c000
	ds_read_b128 v[130:133], v244 offset:32768
	ds_read_b128 v[134:137], v244 offset:33792
	ds_read_b128 v[138:141], v244 offset:34816
	ds_read_b128 v[142:145], v244 offset:35840
	ds_read_b128 v[170:173], v244 offset:49152
	ds_read_b128 v[174:177], v244 offset:50176
	ds_read_b128 v[202:205], v244 offset:51200
	ds_read_b128 v[206:209], v244 offset:52224
	s_add_u32 s12, s12, 0x40000
	s_addc_u32 s13, s13, 0
	s_mov_b32 m0, s63
	ds_read_b128 v[210:213], v200 offset:32768
	ds_read_b128 v[216:219], v200 offset:33792
	ds_read_b128 v[220:223], v200 offset:34816
	ds_read_b128 v[224:227], v200 offset:35840
	ds_read_b128 v[228:231], v200 offset:36864
	ds_read_b128 v[232:235], v200 offset:37888
	ds_read_b128 v[236:239], v200 offset:38912
	ds_read_b128 v[240:243], v200 offset:39936
	global_load_lds_dwordx4 v152, s[12:13]
	s_mov_b32 m0, s64
	s_nop 0
	global_load_lds_dwordx4 v156, s[12:13]
	s_waitcnt vmcnt(8)
	s_waitcnt lgkmcnt(0)
	s_barrier
	s_waitcnt lgkmcnt(0)
	v_mfma_f32_16x16x32_bf16 v[126:129], v[130:133], v[210:213], v[126:129]
	v_mfma_f32_16x16x32_bf16 v[122:125], v[138:141], v[210:213], v[122:125]
	v_mfma_f32_16x16x32_bf16 v[110:113], v[130:133], v[220:223], v[110:113]
	v_mfma_f32_16x16x32_bf16 v[106:109], v[138:141], v[220:223], v[106:109]
	v_mfma_f32_16x16x32_bf16 v[94:97], v[130:133], v[228:231], v[94:97]
	v_mfma_f32_16x16x32_bf16 v[90:93], v[138:141], v[228:231], v[90:93]
	v_mfma_f32_16x16x32_bf16 v[78:81], v[130:133], v[236:239], v[78:81]
	v_mfma_f32_16x16x32_bf16 v[74:77], v[138:141], v[236:239], v[74:77]
	v_mfma_f32_16x16x32_bf16 v[126:129], v[134:137], v[216:219], v[126:129]
	v_mfma_f32_16x16x32_bf16 v[122:125], v[142:145], v[216:219], v[122:125]
	v_mfma_f32_16x16x32_bf16 v[110:113], v[134:137], v[224:227], v[110:113]
	v_mfma_f32_16x16x32_bf16 v[106:109], v[142:145], v[224:227], v[106:109]
	v_mfma_f32_16x16x32_bf16 v[94:97], v[134:137], v[232:235], v[94:97]
	v_mfma_f32_16x16x32_bf16 v[90:93], v[142:145], v[232:235], v[90:93]
	v_mfma_f32_16x16x32_bf16 v[78:81], v[134:137], v[240:243], v[78:81]
	v_mfma_f32_16x16x32_bf16 v[74:77], v[142:145], v[240:243], v[74:77]
	v_mfma_f32_16x16x32_bf16 v[118:121], v[170:173], v[210:213], v[118:121]
	v_mfma_f32_16x16x32_bf16 v[114:117], v[202:205], v[210:213], v[114:117]
	v_mfma_f32_16x16x32_bf16 v[102:105], v[170:173], v[220:223], v[102:105]
	v_mfma_f32_16x16x32_bf16 v[98:101], v[202:205], v[220:223], v[98:101]
	v_mfma_f32_16x16x32_bf16 v[86:89], v[170:173], v[228:231], v[86:89]
	v_mfma_f32_16x16x32_bf16 v[82:85], v[202:205], v[228:231], v[82:85]
	v_mfma_f32_16x16x32_bf16 v[70:73], v[170:173], v[236:239], v[70:73]
	v_mfma_f32_16x16x32_bf16 v[66:69], v[202:205], v[236:239], v[66:69]
	v_mfma_f32_16x16x32_bf16 v[118:121], v[174:177], v[216:219], v[118:121]
	v_mfma_f32_16x16x32_bf16 v[114:117], v[206:209], v[216:219], v[114:117]
	v_mfma_f32_16x16x32_bf16 v[102:105], v[174:177], v[224:227], v[102:105]
	v_mfma_f32_16x16x32_bf16 v[98:101], v[206:209], v[224:227], v[98:101]
	v_mfma_f32_16x16x32_bf16 v[86:89], v[174:177], v[232:235], v[86:89]
	v_mfma_f32_16x16x32_bf16 v[82:85], v[206:209], v[232:235], v[82:85]
	v_mfma_f32_16x16x32_bf16 v[70:73], v[174:177], v[240:243], v[70:73]
	v_mfma_f32_16x16x32_bf16 v[66:69], v[206:209], v[240:243], v[66:69]
	s_barrier
	s_add_i32 m0, s30, s61
	s_add_u32 s42, s10, 0x80
	s_addc_u32 s43, s11, 0
	ds_read_b128 v[210:213], v200 offset:49152
	ds_read_b128 v[216:219], v200 offset:50176
	ds_read_b128 v[220:223], v200 offset:51200
	ds_read_b128 v[224:227], v200 offset:52224
	ds_read_b128 v[228:231], v200 offset:53248
	ds_read_b128 v[232:235], v200 offset:54272
	ds_read_b128 v[236:239], v200 offset:55296
	ds_read_b128 v[240:243], v200 offset:56320
	global_load_lds_dwordx4 v154, s[42:43]
	s_add_i32 m0, m0, 0x2000
	s_add_u32 s10, s10, 0x40080
	s_addc_u32 s11, s11, 0
	global_load_lds_dwordx4 v158, s[42:43]
	s_add_i32 m0, s31, s61
	s_add_u32 s42, s12, 0xfffc0080
	s_addc_u32 s43, s13, -1
	global_load_lds_dwordx4 v154, s[10:11]
	s_add_i32 m0, m0, 0x2000
	s_nop 0
	global_load_lds_dwordx4 v158, s[10:11]
	s_mov_b32 m0, s66
	s_nop 0
	global_load_lds_dwordx4 v152, s[42:43]
	s_mov_b32 m0, s67
	s_add_i32 s12, s31, s61
	global_load_lds_dwordx4 v156, s[42:43]
	s_add_i32 s29, s29, 2
	s_add_u32 s8, s8, 0x100
	s_addc_u32 s9, s9, 0
	s_add_u32 s27, s27, 0x100
	s_addc_u32 s28, s28, 0
	s_cmp_gt_u32 s29, 13
	s_cbranch_scc1 .Lk1_skip
	s_add_u32 s10, s8, 0xfffc0080
	s_addc_u32 s11, s9, -1
	s_add_i32 s30, 0, 0x10000
	s_cmp_eq_u32 s29, 12
	s_cselect_b32 s13, s3, s11
	s_cselect_b32 s12, s24, s10
	s_cselect_b32 s11, s25, s28
	s_cselect_b32 s10, s26, s27
	s_add_i32 s31, 0, 0x14000

.LBB0_640:
	ds_read_b128 v[144:147], v153
	ds_read_b128 v[156:159], v153 offset:1024
	ds_read_b128 v[160:163], v153 offset:2048
	ds_read_b128 v[164:167], v153 offset:3072
	ds_read_b128 v[168:171], v154
	ds_read_b128 v[172:175], v154 offset:1024
	ds_read_b128 v[176:179], v154 offset:2048
	ds_read_b128 v[180:183], v154 offset:3072
	s_add_u32 s28, s12, 0xfffc0080
	s_addc_u32 s29, s13, -1
	s_cmp_eq_u32 s27, 12
	s_cselect_b32 s57, s11, s29
	s_cselect_b32 s56, s14, s28
	s_cselect_b32 s55, s15, s26
	s_cselect_b32 s54, s24, s25
	s_add_i32 m0, s19, 0xc000
	ds_read_b128 v[184:187], v155
	ds_read_b128 v[188:191], v155 offset:1024
	ds_read_b128 v[192:195], v155 offset:2048
	ds_read_b128 v[196:199], v155 offset:3072
	ds_read_b128 v[200:203], v155 offset:4096
	ds_read_b128 v[204:207], v155 offset:5120
	ds_read_b128 v[208:211], v155 offset:6144
	ds_read_b128 v[216:219], v155 offset:7168
	global_load_lds_dwordx4 v136, s[12:13]
	s_add_i32 m0, s19, 0xe000
	s_nop 0
	global_load_lds_dwordx4 v138, s[12:13]
	s_waitcnt vmcnt(8)
	s_waitcnt lgkmcnt(0)
	s_barrier
	s_waitcnt lgkmcnt(0)
	v_mfma_f32_16x16x32_bf16 v[124:127], v[144:147], v[184:187], v[124:127]
	v_mfma_f32_16x16x32_bf16 v[120:123], v[160:163], v[184:187], v[120:123]
	v_mfma_f32_16x16x32_bf16 v[108:111], v[144:147], v[192:195], v[108:111]
	v_mfma_f32_16x16x32_bf16 v[104:107], v[160:163], v[192:195], v[104:107]
	v_mfma_f32_16x16x32_bf16 v[92:95], v[144:147], v[200:203], v[92:95]
	v_mfma_f32_16x16x32_bf16 v[88:91], v[160:163], v[200:203], v[88:91]
	v_mfma_f32_16x16x32_bf16 v[76:79], v[144:147], v[208:211], v[76:79]
	v_mfma_f32_16x16x32_bf16 v[72:75], v[160:163], v[208:211], v[72:75]
	v_mfma_f32_16x16x32_bf16 v[124:127], v[156:159], v[188:191], v[124:127]
	v_mfma_f32_16x16x32_bf16 v[120:123], v[164:167], v[188:191], v[120:123]
	v_mfma_f32_16x16x32_bf16 v[108:111], v[156:159], v[196:199], v[108:111]
	v_mfma_f32_16x16x32_bf16 v[104:107], v[164:167], v[196:199], v[104:107]
	v_mfma_f32_16x16x32_bf16 v[92:95], v[156:159], v[204:207], v[92:95]
	v_mfma_f32_16x16x32_bf16 v[88:91], v[164:167], v[204:207], v[88:91]
	v_mfma_f32_16x16x32_bf16 v[76:79], v[156:159], v[216:219], v[76:79]
	v_mfma_f32_16x16x32_bf16 v[72:75], v[164:167], v[216:219], v[72:75]
	v_mfma_f32_16x16x32_bf16 v[116:119], v[168:171], v[184:187], v[116:119]
	v_mfma_f32_16x16x32_bf16 v[112:115], v[176:179], v[184:187], v[112:115]
	v_mfma_f32_16x16x32_bf16 v[100:103], v[168:171], v[192:195], v[100:103]
	v_mfma_f32_16x16x32_bf16 v[96:99], v[176:179], v[192:195], v[96:99]
	v_mfma_f32_16x16x32_bf16 v[84:87], v[168:171], v[200:203], v[84:87]
	v_mfma_f32_16x16x32_bf16 v[80:83], v[176:179], v[200:203], v[80:83]
	v_mfma_f32_16x16x32_bf16 v[68:71], v[168:171], v[208:211], v[68:71]
	v_mfma_f32_16x16x32_bf16 v[64:67], v[176:179], v[208:211], v[64:67]
	v_mfma_f32_16x16x32_bf16 v[116:119], v[172:175], v[188:191], v[116:119]
	v_mfma_f32_16x16x32_bf16 v[112:115], v[180:183], v[188:191], v[112:115]
	v_mfma_f32_16x16x32_bf16 v[100:103], v[172:175], v[196:199], v[100:103]
	v_mfma_f32_16x16x32_bf16 v[96:99], v[180:183], v[196:199], v[96:99]
	v_mfma_f32_16x16x32_bf16 v[84:87], v[172:175], v[204:207], v[84:87]
	v_mfma_f32_16x16x32_bf16 v[80:83], v[180:183], v[204:207], v[80:83]
	v_mfma_f32_16x16x32_bf16 v[68:71], v[172:175], v[216:219], v[68:71]
	v_mfma_f32_16x16x32_bf16 v[64:67], v[180:183], v[216:219], v[64:67]
	s_barrier
	s_add_i32 s28, s63, s18
	s_mov_b32 m0, s28
	ds_read_b128 v[184:187], v155 offset:16384
	ds_read_b128 v[188:191], v155 offset:17408
	ds_read_b128 v[192:195], v155 offset:18432
	ds_read_b128 v[196:199], v155 offset:19456
	ds_read_b128 v[200:203], v155 offset:20480
	ds_read_b128 v[204:207], v155 offset:21504
	ds_read_b128 v[208:211], v155 offset:22528
	ds_read_b128 v[216:219], v155 offset:23552
	global_load_lds_dwordx4 v130, s[54:55]
	s_add_i32 m0, s28, 0x2000
	s_add_u32 s28, s54, 0x40000
	s_addc_u32 s29, s55, 0
	s_add_i32 s30, s64, s18
	global_load_lds_dwordx4 v134, s[54:55]
	s_mov_b32 m0, s30
	s_nop 0
	global_load_lds_dwordx4 v130, s[28:29]
	s_add_i32 m0, s30, 0x2000
	s_nop 0
	global_load_lds_dwordx4 v134, s[28:29]
	s_mov_b32 m0, s19
	s_nop 0
	global_load_lds_dwordx4 v128, s[56:57]
	s_mov_b32 m0, s20
	s_nop 0
	global_load_lds_dwordx4 v132, s[56:57]
	s_waitcnt vmcnt(8)
	s_waitcnt lgkmcnt(0)
	s_barrier
	s_waitcnt lgkmcnt(0)
	v_mfma_f32_16x16x32_bf16 v[60:63], v[144:147], v[184:187], v[60:63]
	v_mfma_f32_16x16x32_bf16 v[56:59], v[160:163], v[184:187], v[56:59]
	v_mfma_f32_16x16x32_bf16 v[44:47], v[144:147], v[192:195], v[44:47]
	v_mfma_f32_16x16x32_bf16 v[40:43], v[160:163], v[192:195], v[40:43]
	v_mfma_f32_16x16x32_bf16 v[28:31], v[144:147], v[200:203], v[28:31]
	v_mfma_f32_16x16x32_bf16 v[24:27], v[160:163], v[200:203], v[24:27]
	v_mfma_f32_16x16x32_bf16 v[12:15], v[144:147], v[208:211], v[12:15]
	v_mfma_f32_16x16x32_bf16 v[8:11], v[160:163], v[208:211], v[8:11]
	v_mfma_f32_16x16x32_bf16 v[60:63], v[156:159], v[188:191], v[60:63]
	v_mfma_f32_16x16x32_bf16 v[56:59], v[164:167], v[188:191], v[56:59]
	v_mfma_f32_16x16x32_bf16 v[44:47], v[156:159], v[196:199], v[44:47]
	v_mfma_f32_16x16x32_bf16 v[40:43], v[164:167], v[196:199], v[40:43]
	v_mfma_f32_16x16x32_bf16 v[28:31], v[156:159], v[204:207], v[28:31]
	v_mfma_f32_16x16x32_bf16 v[24:27], v[164:167], v[204:207], v[24:27]
	v_mfma_f32_16x16x32_bf16 v[12:15], v[156:159], v[216:219], v[12:15]
	v_mfma_f32_16x16x32_bf16 v[8:11], v[164:167], v[216:219], v[8:11]
	v_mfma_f32_16x16x32_bf16 v[52:55], v[168:171], v[184:187], v[52:55]
	v_mfma_f32_16x16x32_bf16 v[48:51], v[176:179], v[184:187], v[48:51]
	v_mfma_f32_16x16x32_bf16 v[36:39], v[168:171], v[192:195], v[36:39]
	v_mfma_f32_16x16x32_bf16 v[32:35], v[176:179], v[192:195], v[32:35]
	v_mfma_f32_16x16x32_bf16 v[20:23], v[168:171], v[200:203], v[20:23]
	v_mfma_f32_16x16x32_bf16 v[16:19], v[176:179], v[200:203], v[16:19]
	v_mfma_f32_16x16x32_bf16 v[4:7], v[168:171], v[208:211], v[4:7]
	v_mfma_f32_16x16x32_bf16 v[0:3], v[176:179], v[208:211], v[0:3]
	v_mfma_f32_16x16x32_bf16 v[52:55], v[172:175], v[188:191], v[52:55]
	v_mfma_f32_16x16x32_bf16 v[48:51], v[180:183], v[188:191], v[48:51]
	v_mfma_f32_16x16x32_bf16 v[36:39], v[172:175], v[196:199], v[36:39]
	v_mfma_f32_16x16x32_bf16 v[32:35], v[180:183], v[196:199], v[32:35]
	v_mfma_f32_16x16x32_bf16 v[20:23], v[172:175], v[204:207], v[20:23]
	v_mfma_f32_16x16x32_bf16 v[16:19], v[180:183], v[204:207], v[16:19]
	v_mfma_f32_16x16x32_bf16 v[4:7], v[172:175], v[216:219], v[4:7]
	v_mfma_f32_16x16x32_bf16 v[0:3], v[180:183], v[216:219], v[0:3]
	s_barrier
	s_add_i32 s30, 0, 0x18000
	s_add_i32 s31, 0, 0x1c000
	ds_read_b128 v[144:147], v153 offset:32768
	ds_read_b128 v[156:159], v153 offset:33792
	ds_read_b128 v[160:163], v153 offset:34816
	ds_read_b128 v[164:167], v153 offset:35840
	ds_read_b128 v[168:171], v153 offset:49152
	ds_read_b128 v[172:175], v153 offset:50176
	ds_read_b128 v[176:179], v153 offset:51200
	ds_read_b128 v[180:183], v153 offset:52224
	s_add_u32 s28, s56, 0x40000
	s_addc_u32 s29, s57, 0
	s_mov_b32 m0, s21
	ds_read_b128 v[184:187], v155 offset:32768
	ds_read_b128 v[188:191], v155 offset:33792
	ds_read_b128 v[192:195], v155 offset:34816
	ds_read_b128 v[196:199], v155 offset:35840
	ds_read_b128 v[200:203], v155 offset:36864
	ds_read_b128 v[204:207], v155 offset:37888
	ds_read_b128 v[208:211], v155 offset:38912
	ds_read_b128 v[216:219], v155 offset:39936
	global_load_lds_dwordx4 v128, s[28:29]
	s_mov_b32 m0, s22
	s_nop 0
	global_load_lds_dwordx4 v132, s[28:29]
	s_waitcnt vmcnt(8)
	s_waitcnt lgkmcnt(0)
	s_barrier
	s_waitcnt lgkmcnt(0)
	v_mfma_f32_16x16x32_bf16 v[124:127], v[144:147], v[184:187], v[124:127]
	v_mfma_f32_16x16x32_bf16 v[120:123], v[160:163], v[184:187], v[120:123]
	v_mfma_f32_16x16x32_bf16 v[108:111], v[144:147], v[192:195], v[108:111]
	v_mfma_f32_16x16x32_bf16 v[104:107], v[160:163], v[192:195], v[104:107]
	v_mfma_f32_16x16x32_bf16 v[92:95], v[144:147], v[200:203], v[92:95]
	v_mfma_f32_16x16x32_bf16 v[88:91], v[160:163], v[200:203], v[88:91]
	v_mfma_f32_16x16x32_bf16 v[76:79], v[144:147], v[208:211], v[76:79]
	v_mfma_f32_16x16x32_bf16 v[72:75], v[160:163], v[208:211], v[72:75]
	v_mfma_f32_16x16x32_bf16 v[124:127], v[156:159], v[188:191], v[124:127]
	v_mfma_f32_16x16x32_bf16 v[120:123], v[164:167], v[188:191], v[120:123]
	v_mfma_f32_16x16x32_bf16 v[108:111], v[156:159], v[196:199], v[108:111]
	v_mfma_f32_16x16x32_bf16 v[104:107], v[164:167], v[196:199], v[104:107]
	v_mfma_f32_16x16x32_bf16 v[92:95], v[156:159], v[204:207], v[92:95]
	v_mfma_f32_16x16x32_bf16 v[88:91], v[164:167], v[204:207], v[88:91]
	v_mfma_f32_16x16x32_bf16 v[76:79], v[156:159], v[216:219], v[76:79]
	v_mfma_f32_16x16x32_bf16 v[72:75], v[164:167], v[216:219], v[72:75]
	v_mfma_f32_16x16x32_bf16 v[116:119], v[168:171], v[184:187], v[116:119]
	v_mfma_f32_16x16x32_bf16 v[112:115], v[176:179], v[184:187], v[112:115]
	v_mfma_f32_16x16x32_bf16 v[100:103], v[168:171], v[192:195], v[100:103]
	v_mfma_f32_16x16x32_bf16 v[96:99], v[176:179], v[192:195], v[96:99]
	v_mfma_f32_16x16x32_bf16 v[84:87], v[168:171], v[200:203], v[84:87]
	v_mfma_f32_16x16x32_bf16 v[80:83], v[176:179], v[200:203], v[80:83]
	v_mfma_f32_16x16x32_bf16 v[68:71], v[168:171], v[208:211], v[68:71]
	v_mfma_f32_16x16x32_bf16 v[64:67], v[176:179], v[208:211], v[64:67]
	v_mfma_f32_16x16x32_bf16 v[116:119], v[172:175], v[188:191], v[116:119]
	v_mfma_f32_16x16x32_bf16 v[112:115], v[180:183], v[188:191], v[112:115]
	v_mfma_f32_16x16x32_bf16 v[100:103], v[172:175], v[196:199], v[100:103]
	v_mfma_f32_16x16x32_bf16 v[96:99], v[180:183], v[196:199], v[96:99]
	v_mfma_f32_16x16x32_bf16 v[84:87], v[172:175], v[204:207], v[84:87]
	v_mfma_f32_16x16x32_bf16 v[80:83], v[180:183], v[204:207], v[80:83]
	v_mfma_f32_16x16x32_bf16 v[68:71], v[172:175], v[216:219], v[68:71]
	v_mfma_f32_16x16x32_bf16 v[64:67], v[180:183], v[216:219], v[64:67]
	s_barrier
	s_add_i32 m0, s30, s18
	s_add_u32 s28, s54, 0x80
	s_addc_u32 s29, s55, 0
	ds_read_b128 v[184:187], v155 offset:49152
	ds_read_b128 v[188:191], v155 offset:50176
	ds_read_b128 v[192:195], v155 offset:51200
	ds_read_b128 v[196:199], v155 offset:52224
	ds_read_b128 v[200:203], v155 offset:53248
	ds_read_b128 v[204:207], v155 offset:54272
	ds_read_b128 v[208:211], v155 offset:55296
	ds_read_b128 v[216:219], v155 offset:56320
	global_load_lds_dwordx4 v130, s[28:29]
	s_add_i32 m0, m0, 0x2000
	s_add_i32 s30, s31, s18
	global_load_lds_dwordx4 v134, s[28:29]
	s_add_u32 s28, s28, 0x40000
	s_addc_u32 s29, s29, 0
	s_mov_b32 m0, s30
	s_nop 0
	global_load_lds_dwordx4 v130, s[28:29]
	s_add_i32 m0, s30, 0x2000
	s_nop 0
	global_load_lds_dwordx4 v134, s[28:29]
	s_add_u32 s28, s56, 0x80
	s_addc_u32 s29, s57, 0
	s_mov_b32 m0, s33
	s_nop 0
	global_load_lds_dwordx4 v128, s[28:29]
	s_mov_b32 m0, s58
	s_nop 0
	global_load_lds_dwordx4 v132, s[28:29]
	s_add_u32 s28, s54, 0x40080
	s_addc_u32 s29, s55, 0
	s_waitcnt vmcnt(8)
	s_waitcnt lgkmcnt(0)
	s_barrier
	s_waitcnt lgkmcnt(0)
	v_mfma_f32_16x16x32_bf16 v[60:63], v[144:147], v[184:187], v[60:63]
	v_mfma_f32_16x16x32_bf16 v[56:59], v[160:163], v[184:187], v[56:59]
	v_mfma_f32_16x16x32_bf16 v[44:47], v[144:147], v[192:195], v[44:47]
	v_mfma_f32_16x16x32_bf16 v[40:43], v[160:163], v[192:195], v[40:43]
	v_mfma_f32_16x16x32_bf16 v[28:31], v[144:147], v[200:203], v[28:31]
	v_mfma_f32_16x16x32_bf16 v[24:27], v[160:163], v[200:203], v[24:27]
	v_mfma_f32_16x16x32_bf16 v[12:15], v[144:147], v[208:211], v[12:15]
	v_mfma_f32_16x16x32_bf16 v[8:11], v[160:163], v[208:211], v[8:11]
	v_mfma_f32_16x16x32_bf16 v[60:63], v[156:159], v[188:191], v[60:63]
	v_mfma_f32_16x16x32_bf16 v[56:59], v[164:167], v[188:191], v[56:59]
	v_mfma_f32_16x16x32_bf16 v[44:47], v[156:159], v[196:199], v[44:47]
	v_mfma_f32_16x16x32_bf16 v[40:43], v[164:167], v[196:199], v[40:43]
	v_mfma_f32_16x16x32_bf16 v[28:31], v[156:159], v[204:207], v[28:31]
	v_mfma_f32_16x16x32_bf16 v[24:27], v[164:167], v[204:207], v[24:27]
	v_mfma_f32_16x16x32_bf16 v[12:15], v[156:159], v[216:219], v[12:15]
	v_mfma_f32_16x16x32_bf16 v[8:11], v[164:167], v[216:219], v[8:11]
	v_mfma_f32_16x16x32_bf16 v[52:55], v[168:171], v[184:187], v[52:55]
	v_mfma_f32_16x16x32_bf16 v[48:51], v[176:179], v[184:187], v[48:51]
	v_mfma_f32_16x16x32_bf16 v[36:39], v[168:171], v[192:195], v[36:39]
	v_mfma_f32_16x16x32_bf16 v[32:35], v[176:179], v[192:195], v[32:35]
	v_mfma_f32_16x16x32_bf16 v[20:23], v[168:171], v[200:203], v[20:23]
	v_mfma_f32_16x16x32_bf16 v[16:19], v[176:179], v[200:203], v[16:19]
	v_mfma_f32_16x16x32_bf16 v[4:7], v[168:171], v[208:211], v[4:7]
	v_mfma_f32_16x16x32_bf16 v[0:3], v[176:179], v[208:211], v[0:3]
	v_mfma_f32_16x16x32_bf16 v[52:55], v[172:175], v[188:191], v[52:55]
	v_mfma_f32_16x16x32_bf16 v[48:51], v[180:183], v[188:191], v[48:51]
	v_mfma_f32_16x16x32_bf16 v[36:39], v[172:175], v[196:199], v[36:39]
	v_mfma_f32_16x16x32_bf16 v[32:35], v[180:183], v[196:199], v[32:35]
	v_mfma_f32_16x16x32_bf16 v[20:23], v[172:175], v[204:207], v[20:23]
	v_mfma_f32_16x16x32_bf16 v[16:19], v[180:183], v[204:207], v[16:19]
	v_mfma_f32_16x16x32_bf16 v[4:7], v[172:175], v[216:219], v[4:7]
	v_mfma_f32_16x16x32_bf16 v[0:3], v[180:183], v[216:219], v[0:3]
	s_barrier
	s_add_i32 s27, s27, 2
	s_add_u32 s12, s12, 0x100
	s_addc_u32 s13, s13, 0
	s_add_u32 s25, s25, 0x100
	s_addc_u32 s26, s26, 0
	s_cmp_gt_u32 s27, 13
	s_cbranch_scc0 .LBB0_640
	s_setprio 0
	s_and_b64 vcc, exec, s[8:9]
	s_cbranch_vccz .LBB0_643
	s_barrier

.LBB0_744:
	ds_read_b128 v[80:83], v226
	ds_read_b128 v[84:87], v226 offset:1024
	ds_read_b128 v[88:91], v226 offset:2048
	ds_read_b128 v[92:95], v226 offset:3072
	ds_read_b128 v[128:131], v227
	ds_read_b128 v[132:135], v227 offset:1024
	ds_read_b128 v[152:155], v227 offset:2048
	ds_read_b128 v[156:159], v227 offset:3072
	s_add_u32 s26, s46, 0xfffc0080
	s_addc_u32 s27, s47, -1
	s_cmp_eq_u32 s25, 12
	s_cselect_b32 s89, s11, s27
	s_cselect_b32 s88, s14, s26
	s_cselect_b32 s49, s15, s24
	s_cselect_b32 s48, s16, s17
	s_add_i32 m0, s13, 0xc000
	ds_read_b128 v[160:163], v228
	ds_read_b128 v[164:167], v228 offset:1024
	ds_read_b128 v[168:171], v228 offset:2048
	ds_read_b128 v[172:175], v228 offset:3072
	ds_read_b128 v[192:195], v228 offset:4096
	ds_read_b128 v[196:199], v228 offset:5120
	ds_read_b128 v[200:203], v228 offset:6144
	ds_read_b128 v[204:207], v228 offset:7168
	global_load_lds_dwordx4 v184, s[46:47]
	s_add_i32 m0, s13, 0xe000
	s_nop 0
	global_load_lds_dwordx4 v186, s[46:47]
	s_waitcnt vmcnt(8)
	s_waitcnt lgkmcnt(0)
	s_barrier
	s_waitcnt lgkmcnt(0)
	v_mfma_f32_16x16x32_bf16 v[76:79], v[80:83], v[160:163], v[76:79]
	v_mfma_f32_16x16x32_bf16 v[64:67], v[88:91], v[160:163], v[64:67]
	v_mfma_f32_16x16x32_bf16 v[148:151], v[80:83], v[168:171], v[148:151]
	v_mfma_f32_16x16x32_bf16 v[140:143], v[88:91], v[168:171], v[140:143]
	v_mfma_f32_16x16x32_bf16 v[124:127], v[80:83], v[192:195], v[124:127]
	v_mfma_f32_16x16x32_bf16 v[120:123], v[88:91], v[192:195], v[120:123]
	v_mfma_f32_16x16x32_bf16 v[72:75], v[80:83], v[200:203], v[72:75]
	v_mfma_f32_16x16x32_bf16 v[60:63], v[88:91], v[200:203], v[60:63]
	v_mfma_f32_16x16x32_bf16 v[76:79], v[84:87], v[164:167], v[76:79]
	v_mfma_f32_16x16x32_bf16 v[64:67], v[92:95], v[164:167], v[64:67]
	v_mfma_f32_16x16x32_bf16 v[148:151], v[84:87], v[172:175], v[148:151]
	v_mfma_f32_16x16x32_bf16 v[140:143], v[92:95], v[172:175], v[140:143]
	v_mfma_f32_16x16x32_bf16 v[124:127], v[84:87], v[196:199], v[124:127]
	v_mfma_f32_16x16x32_bf16 v[120:123], v[92:95], v[196:199], v[120:123]
	v_mfma_f32_16x16x32_bf16 v[72:75], v[84:87], v[204:207], v[72:75]
	v_mfma_f32_16x16x32_bf16 v[60:63], v[92:95], v[204:207], v[60:63]
	v_mfma_f32_16x16x32_bf16 v[144:147], v[128:131], v[160:163], v[144:147]
	v_mfma_f32_16x16x32_bf16 v[136:139], v[152:155], v[160:163], v[136:139]
	v_mfma_f32_16x16x32_bf16 v[116:119], v[128:131], v[168:171], v[116:119]
	v_mfma_f32_16x16x32_bf16 v[112:115], v[152:155], v[168:171], v[112:115]
	v_mfma_f32_16x16x32_bf16 v[108:111], v[128:131], v[192:195], v[108:111]
	v_mfma_f32_16x16x32_bf16 v[104:107], v[152:155], v[192:195], v[104:107]
	v_mfma_f32_16x16x32_bf16 v[100:103], v[128:131], v[200:203], v[100:103]
	v_mfma_f32_16x16x32_bf16 v[96:99], v[152:155], v[200:203], v[96:99]
	v_mfma_f32_16x16x32_bf16 v[144:147], v[132:135], v[164:167], v[144:147]
	v_mfma_f32_16x16x32_bf16 v[136:139], v[156:159], v[164:167], v[136:139]
	v_mfma_f32_16x16x32_bf16 v[116:119], v[132:135], v[172:175], v[116:119]
	v_mfma_f32_16x16x32_bf16 v[112:115], v[156:159], v[172:175], v[112:115]
	v_mfma_f32_16x16x32_bf16 v[108:111], v[132:135], v[196:199], v[108:111]
	v_mfma_f32_16x16x32_bf16 v[104:107], v[156:159], v[196:199], v[104:107]
	v_mfma_f32_16x16x32_bf16 v[100:103], v[132:135], v[204:207], v[100:103]
	v_mfma_f32_16x16x32_bf16 v[96:99], v[156:159], v[204:207], v[96:99]
	s_barrier
	s_add_i32 s26, s3, s20
	s_mov_b32 m0, s26
	ds_read_b128 v[160:163], v228 offset:16384
	ds_read_b128 v[164:167], v228 offset:17408
	ds_read_b128 v[168:171], v228 offset:18432
	ds_read_b128 v[172:175], v228 offset:19456
	ds_read_b128 v[192:195], v228 offset:20480
	ds_read_b128 v[196:199], v228 offset:21504
	ds_read_b128 v[200:203], v228 offset:22528
	ds_read_b128 v[204:207], v228 offset:23552
	global_load_lds_dwordx4 v178, s[48:49]
	s_add_i32 m0, s26, 0x2000
	s_add_u32 s26, s48, 0x40000
	s_addc_u32 s27, s49, 0
	s_add_i32 s28, s93, s20
	global_load_lds_dwordx4 v182, s[48:49]
	s_mov_b32 m0, s28
	s_nop 0
	global_load_lds_dwordx4 v178, s[26:27]
	s_add_i32 m0, s28, 0x2000
	s_nop 0
	global_load_lds_dwordx4 v182, s[26:27]
	s_mov_b32 m0, s13
	s_nop 0
	global_load_lds_dwordx4 v176, s[88:89]
	s_mov_b32 m0, s21
	s_nop 0
	global_load_lds_dwordx4 v180, s[88:89]
	s_waitcnt vmcnt(8)
	s_waitcnt lgkmcnt(0)
	s_barrier
	s_waitcnt lgkmcnt(0)
	v_mfma_f32_16x16x32_bf16 v[68:71], v[80:83], v[160:163], v[68:71]
	v_mfma_f32_16x16x32_bf16 v[36:39], v[88:91], v[160:163], v[36:39]
	v_mfma_f32_16x16x32_bf16 v[52:55], v[80:83], v[168:171], v[52:55]
	v_mfma_f32_16x16x32_bf16 v[44:47], v[88:91], v[168:171], v[44:47]
	v_mfma_f32_16x16x32_bf16 v[28:31], v[80:83], v[192:195], v[28:31]
	v_mfma_f32_16x16x32_bf16 v[24:27], v[88:91], v[192:195], v[24:27]
	v_mfma_f32_16x16x32_bf16 v[56:59], v[80:83], v[200:203], v[56:59]
	v_mfma_f32_16x16x32_bf16 v[32:35], v[88:91], v[200:203], v[32:35]
	v_mfma_f32_16x16x32_bf16 v[68:71], v[84:87], v[164:167], v[68:71]
	v_mfma_f32_16x16x32_bf16 v[36:39], v[92:95], v[164:167], v[36:39]
	v_mfma_f32_16x16x32_bf16 v[52:55], v[84:87], v[172:175], v[52:55]
	v_mfma_f32_16x16x32_bf16 v[44:47], v[92:95], v[172:175], v[44:47]
	v_mfma_f32_16x16x32_bf16 v[28:31], v[84:87], v[196:199], v[28:31]
	v_mfma_f32_16x16x32_bf16 v[24:27], v[92:95], v[196:199], v[24:27]
	v_mfma_f32_16x16x32_bf16 v[56:59], v[84:87], v[204:207], v[56:59]
	v_mfma_f32_16x16x32_bf16 v[32:35], v[92:95], v[204:207], v[32:35]
	v_mfma_f32_16x16x32_bf16 v[48:51], v[128:131], v[160:163], v[48:51]
	v_mfma_f32_16x16x32_bf16 v[40:43], v[152:155], v[160:163], v[40:43]
	v_mfma_f32_16x16x32_bf16 v[20:23], v[128:131], v[168:171], v[20:23]
	v_mfma_f32_16x16x32_bf16 v[16:19], v[152:155], v[168:171], v[16:19]
	v_mfma_f32_16x16x32_bf16 v[12:15], v[128:131], v[192:195], v[12:15]
	v_mfma_f32_16x16x32_bf16 v[8:11], v[152:155], v[192:195], v[8:11]
	v_mfma_f32_16x16x32_bf16 v[4:7], v[128:131], v[200:203], v[4:7]
	v_mfma_f32_16x16x32_bf16 v[0:3], v[152:155], v[200:203], v[0:3]
	v_mfma_f32_16x16x32_bf16 v[48:51], v[132:135], v[164:167], v[48:51]
	v_mfma_f32_16x16x32_bf16 v[40:43], v[156:159], v[164:167], v[40:43]
	v_mfma_f32_16x16x32_bf16 v[20:23], v[132:135], v[172:175], v[20:23]
	v_mfma_f32_16x16x32_bf16 v[16:19], v[156:159], v[172:175], v[16:19]
	v_mfma_f32_16x16x32_bf16 v[12:15], v[132:135], v[196:199], v[12:15]
	v_mfma_f32_16x16x32_bf16 v[8:11], v[156:159], v[196:199], v[8:11]
	v_mfma_f32_16x16x32_bf16 v[4:7], v[132:135], v[204:207], v[4:7]
	v_mfma_f32_16x16x32_bf16 v[0:3], v[156:159], v[204:207], v[0:3]
	s_barrier
	s_add_i32 s28, 0, 0x18000
	s_add_i32 s29, 0, 0x1c000
	ds_read_b128 v[80:83], v226 offset:32768
	ds_read_b128 v[84:87], v226 offset:33792
	ds_read_b128 v[88:91], v226 offset:34816
	ds_read_b128 v[92:95], v226 offset:35840
	ds_read_b128 v[128:131], v226 offset:49152
	ds_read_b128 v[132:135], v226 offset:50176
	ds_read_b128 v[152:155], v226 offset:51200
	ds_read_b128 v[156:159], v226 offset:52224
	s_add_u32 s26, s88, 0x40000
	s_addc_u32 s27, s89, 0
	s_mov_b32 m0, s22
	ds_read_b128 v[160:163], v228 offset:32768
	ds_read_b128 v[164:167], v228 offset:33792
	ds_read_b128 v[168:171], v228 offset:34816
	ds_read_b128 v[172:175], v228 offset:35840
	ds_read_b128 v[192:195], v228 offset:36864
	ds_read_b128 v[196:199], v228 offset:37888
	ds_read_b128 v[200:203], v228 offset:38912
	ds_read_b128 v[204:207], v228 offset:39936
	global_load_lds_dwordx4 v176, s[26:27]
	s_mov_b32 m0, s23
	s_nop 0
	global_load_lds_dwordx4 v180, s[26:27]
	s_waitcnt vmcnt(8)
	s_waitcnt lgkmcnt(0)
	s_barrier
	s_waitcnt lgkmcnt(0)
	v_mfma_f32_16x16x32_bf16 v[76:79], v[80:83], v[160:163], v[76:79]
	v_mfma_f32_16x16x32_bf16 v[64:67], v[88:91], v[160:163], v[64:67]
	v_mfma_f32_16x16x32_bf16 v[148:151], v[80:83], v[168:171], v[148:151]
	v_mfma_f32_16x16x32_bf16 v[140:143], v[88:91], v[168:171], v[140:143]
	v_mfma_f32_16x16x32_bf16 v[124:127], v[80:83], v[192:195], v[124:127]
	v_mfma_f32_16x16x32_bf16 v[120:123], v[88:91], v[192:195], v[120:123]
	v_mfma_f32_16x16x32_bf16 v[72:75], v[80:83], v[200:203], v[72:75]
	v_mfma_f32_16x16x32_bf16 v[60:63], v[88:91], v[200:203], v[60:63]
	v_mfma_f32_16x16x32_bf16 v[76:79], v[84:87], v[164:167], v[76:79]
	v_mfma_f32_16x16x32_bf16 v[64:67], v[92:95], v[164:167], v[64:67]
	v_mfma_f32_16x16x32_bf16 v[148:151], v[84:87], v[172:175], v[148:151]
	v_mfma_f32_16x16x32_bf16 v[140:143], v[92:95], v[172:175], v[140:143]
	v_mfma_f32_16x16x32_bf16 v[124:127], v[84:87], v[196:199], v[124:127]
	v_mfma_f32_16x16x32_bf16 v[120:123], v[92:95], v[196:199], v[120:123]
	v_mfma_f32_16x16x32_bf16 v[72:75], v[84:87], v[204:207], v[72:75]
	v_mfma_f32_16x16x32_bf16 v[60:63], v[92:95], v[204:207], v[60:63]
	v_mfma_f32_16x16x32_bf16 v[144:147], v[128:131], v[160:163], v[144:147]
	v_mfma_f32_16x16x32_bf16 v[136:139], v[152:155], v[160:163], v[136:139]
	v_mfma_f32_16x16x32_bf16 v[116:119], v[128:131], v[168:171], v[116:119]
	v_mfma_f32_16x16x32_bf16 v[112:115], v[152:155], v[168:171], v[112:115]
	v_mfma_f32_16x16x32_bf16 v[108:111], v[128:131], v[192:195], v[108:111]
	v_mfma_f32_16x16x32_bf16 v[104:107], v[152:155], v[192:195], v[104:107]
	v_mfma_f32_16x16x32_bf16 v[100:103], v[128:131], v[200:203], v[100:103]
	v_mfma_f32_16x16x32_bf16 v[96:99], v[152:155], v[200:203], v[96:99]
	v_mfma_f32_16x16x32_bf16 v[144:147], v[132:135], v[164:167], v[144:147]
	v_mfma_f32_16x16x32_bf16 v[136:139], v[156:159], v[164:167], v[136:139]
	v_mfma_f32_16x16x32_bf16 v[116:119], v[132:135], v[172:175], v[116:119]
	v_mfma_f32_16x16x32_bf16 v[112:115], v[156:159], v[172:175], v[112:115]
	v_mfma_f32_16x16x32_bf16 v[108:111], v[132:135], v[196:199], v[108:111]
	v_mfma_f32_16x16x32_bf16 v[104:107], v[156:159], v[196:199], v[104:107]
	v_mfma_f32_16x16x32_bf16 v[100:103], v[132:135], v[204:207], v[100:103]
	v_mfma_f32_16x16x32_bf16 v[96:99], v[156:159], v[204:207], v[96:99]
	s_barrier
	s_add_i32 m0, s28, s20
	s_add_u32 s26, s48, 0x80
	s_addc_u32 s27, s49, 0
	ds_read_b128 v[160:163], v228 offset:49152
	ds_read_b128 v[164:167], v228 offset:50176
	ds_read_b128 v[168:171], v228 offset:51200
	ds_read_b128 v[172:175], v228 offset:52224
	ds_read_b128 v[192:195], v228 offset:53248
	ds_read_b128 v[196:199], v228 offset:54272
	ds_read_b128 v[200:203], v228 offset:55296
	ds_read_b128 v[204:207], v228 offset:56320
	global_load_lds_dwordx4 v178, s[26:27]
	s_add_i32 m0, m0, 0x2000
	s_add_i32 s28, s29, s20
	global_load_lds_dwordx4 v182, s[26:27]
	s_add_u32 s26, s26, 0x40000
	s_addc_u32 s27, s27, 0
	s_mov_b32 m0, s28
	s_nop 0
	global_load_lds_dwordx4 v178, s[26:27]
	s_add_i32 m0, s28, 0x2000
	s_nop 0
	global_load_lds_dwordx4 v182, s[26:27]
	s_add_u32 s26, s88, 0x80
	s_addc_u32 s27, s89, 0
	s_mov_b32 m0, s71
	s_nop 0
	global_load_lds_dwordx4 v176, s[26:27]
	s_mov_b32 m0, s73
	s_nop 0
	global_load_lds_dwordx4 v180, s[26:27]
	s_add_u32 s26, s48, 0x40080
	s_addc_u32 s27, s49, 0
	s_waitcnt vmcnt(8)
	s_waitcnt lgkmcnt(0)
	s_barrier
	s_waitcnt lgkmcnt(0)
	v_mfma_f32_16x16x32_bf16 v[68:71], v[80:83], v[160:163], v[68:71]
	v_mfma_f32_16x16x32_bf16 v[36:39], v[88:91], v[160:163], v[36:39]
	v_mfma_f32_16x16x32_bf16 v[52:55], v[80:83], v[168:171], v[52:55]
	v_mfma_f32_16x16x32_bf16 v[44:47], v[88:91], v[168:171], v[44:47]
	v_mfma_f32_16x16x32_bf16 v[28:31], v[80:83], v[192:195], v[28:31]
	v_mfma_f32_16x16x32_bf16 v[24:27], v[88:91], v[192:195], v[24:27]
	v_mfma_f32_16x16x32_bf16 v[56:59], v[80:83], v[200:203], v[56:59]
	v_mfma_f32_16x16x32_bf16 v[32:35], v[88:91], v[200:203], v[32:35]
	v_mfma_f32_16x16x32_bf16 v[68:71], v[84:87], v[164:167], v[68:71]
	v_mfma_f32_16x16x32_bf16 v[36:39], v[92:95], v[164:167], v[36:39]
	v_mfma_f32_16x16x32_bf16 v[52:55], v[84:87], v[172:175], v[52:55]
	v_mfma_f32_16x16x32_bf16 v[44:47], v[92:95], v[172:175], v[44:47]
	v_mfma_f32_16x16x32_bf16 v[28:31], v[84:87], v[196:199], v[28:31]
	v_mfma_f32_16x16x32_bf16 v[24:27], v[92:95], v[196:199], v[24:27]
	v_mfma_f32_16x16x32_bf16 v[56:59], v[84:87], v[204:207], v[56:59]
	v_mfma_f32_16x16x32_bf16 v[32:35], v[92:95], v[204:207], v[32:35]
	v_mfma_f32_16x16x32_bf16 v[48:51], v[128:131], v[160:163], v[48:51]
	v_mfma_f32_16x16x32_bf16 v[40:43], v[152:155], v[160:163], v[40:43]
	v_mfma_f32_16x16x32_bf16 v[20:23], v[128:131], v[168:171], v[20:23]
	v_mfma_f32_16x16x32_bf16 v[16:19], v[152:155], v[168:171], v[16:19]
	v_mfma_f32_16x16x32_bf16 v[12:15], v[128:131], v[192:195], v[12:15]
	v_mfma_f32_16x16x32_bf16 v[8:11], v[152:155], v[192:195], v[8:11]
	v_mfma_f32_16x16x32_bf16 v[4:7], v[128:131], v[200:203], v[4:7]
	v_mfma_f32_16x16x32_bf16 v[0:3], v[152:155], v[200:203], v[0:3]
	v_mfma_f32_16x16x32_bf16 v[48:51], v[132:135], v[164:167], v[48:51]
	v_mfma_f32_16x16x32_bf16 v[40:43], v[156:159], v[164:167], v[40:43]
	v_mfma_f32_16x16x32_bf16 v[20:23], v[132:135], v[172:175], v[20:23]
	v_mfma_f32_16x16x32_bf16 v[16:19], v[156:159], v[172:175], v[16:19]
	v_mfma_f32_16x16x32_bf16 v[12:15], v[132:135], v[196:199], v[12:15]
	v_mfma_f32_16x16x32_bf16 v[8:11], v[156:159], v[196:199], v[8:11]
	v_mfma_f32_16x16x32_bf16 v[4:7], v[132:135], v[204:207], v[4:7]
	v_mfma_f32_16x16x32_bf16 v[0:3], v[156:159], v[204:207], v[0:3]
	s_barrier
	s_add_i32 s25, s25, 2
	s_add_u32 s46, s46, 0x100
	s_addc_u32 s47, s47, 0
	s_add_u32 s17, s17, 0x100
	s_addc_u32 s24, s24, 0
	s_cmp_gt_u32 s25, 13
	s_cbranch_scc0 .LBB0_744
	s_setprio 0
	v_mov_b32_e32 v80, v214
	s_movk_i32 s14, 0x100
	s_lshl_b32 s11, s10, 8
	s_nop 0
	s_cmp_eq_u32 s10, s98
	s_cbranch_scc1 .Lp8_rsl_keep1
	v_cmp_gt_i32_e32 vcc, s14, v80
	s_and_saveexec_b64 s[46:47], vcc
	s_cbranch_execz .Lp8_noss
	v_add_u32_e32 v82, s11, v80
	v_ashrrev_i32_e32 v83, 31, v82
	v_lshlrev_b64 v[82:83], 6, v[82:83]
	v_lshl_add_u64 v[94:95], s[0:1], 0, v[82:83]
	global_load_dwordx4 v[82:85], v[94:95], off
	global_load_dwordx4 v[86:89], v[94:95], off offset:16
	global_load_dwordx4 v[90:93], v[94:95], off offset:32
	global_load_dwordx4 v[128:131], v[94:95], off offset:48

.LBB0_955:
	ds_read_b128 v[128:131], v197
	ds_read_b128 v[132:135], v197 offset:1024
	ds_read_b128 v[136:139], v197 offset:2048
	ds_read_b128 v[140:143], v197 offset:3072
	ds_read_b128 v[144:147], v198
	ds_read_b128 v[148:151], v198 offset:1024
	ds_read_b128 v[168:171], v198 offset:2048
	ds_read_b128 v[172:175], v198 offset:3072
	s_add_u32 s42, s44, 0x100
	s_addc_u32 s43, s45, 0
	s_cmp_eq_u32 s15, 40
	s_cselect_b32 s53, s9, s43
	s_cselect_b32 s52, s8, s42
	s_cselect_b32 s47, s11, s14
	s_cselect_b32 s46, s10, s13
	v_lshl_add_u64 v[176:177], s[44:45], 0, v[160:161]
	s_add_i32 m0, s18, 0xc000
	ds_read_b128 v[202:205], v199
	ds_read_b128 v[206:209], v199 offset:1024
	ds_read_b128 v[210:213], v199 offset:2048
	ds_read_b128 v[216:219], v199 offset:3072
	ds_read_b128 v[220:223], v199 offset:4096
	ds_read_b128 v[224:227], v199 offset:5120
	ds_read_b128 v[228:231], v199 offset:6144
	ds_read_b128 v[232:235], v199 offset:7168
	global_load_lds_dwordx4 v[176:177], off
	v_lshl_add_u64 v[176:177], s[44:45], 0, v[162:163]
	s_add_i32 m0, s18, 0xe000
	s_nop 0
	global_load_lds_dwordx4 v[176:177], off
	s_waitcnt vmcnt(8)
	s_waitcnt lgkmcnt(0)
	s_barrier
	s_waitcnt lgkmcnt(0)
	v_mfma_f32_16x16x32_bf16 v[124:127], v[128:131], v[202:205], v[124:127]
	v_mfma_f32_16x16x32_bf16 v[120:123], v[136:139], v[202:205], v[120:123]
	v_mfma_f32_16x16x32_bf16 v[108:111], v[128:131], v[210:213], v[108:111]
	v_mfma_f32_16x16x32_bf16 v[104:107], v[136:139], v[210:213], v[104:107]
	v_mfma_f32_16x16x32_bf16 v[92:95], v[128:131], v[220:223], v[92:95]
	v_mfma_f32_16x16x32_bf16 v[88:91], v[136:139], v[220:223], v[88:91]
	v_mfma_f32_16x16x32_bf16 v[76:79], v[128:131], v[228:231], v[76:79]
	v_mfma_f32_16x16x32_bf16 v[72:75], v[136:139], v[228:231], v[72:75]
	v_mfma_f32_16x16x32_bf16 v[124:127], v[132:135], v[206:209], v[124:127]
	v_mfma_f32_16x16x32_bf16 v[120:123], v[140:143], v[206:209], v[120:123]
	v_mfma_f32_16x16x32_bf16 v[108:111], v[132:135], v[216:219], v[108:111]
	v_mfma_f32_16x16x32_bf16 v[104:107], v[140:143], v[216:219], v[104:107]
	v_mfma_f32_16x16x32_bf16 v[92:95], v[132:135], v[224:227], v[92:95]
	v_mfma_f32_16x16x32_bf16 v[88:91], v[140:143], v[224:227], v[88:91]
	v_mfma_f32_16x16x32_bf16 v[76:79], v[132:135], v[232:235], v[76:79]
	v_mfma_f32_16x16x32_bf16 v[72:75], v[140:143], v[232:235], v[72:75]
	v_mfma_f32_16x16x32_bf16 v[116:119], v[144:147], v[202:205], v[116:119]
	v_mfma_f32_16x16x32_bf16 v[112:115], v[168:171], v[202:205], v[112:115]
	v_mfma_f32_16x16x32_bf16 v[100:103], v[144:147], v[210:213], v[100:103]
	v_mfma_f32_16x16x32_bf16 v[96:99], v[168:171], v[210:213], v[96:99]
	v_mfma_f32_16x16x32_bf16 v[84:87], v[144:147], v[220:223], v[84:87]
	v_mfma_f32_16x16x32_bf16 v[80:83], v[168:171], v[220:223], v[80:83]
	v_mfma_f32_16x16x32_bf16 v[68:71], v[144:147], v[228:231], v[68:71]
	v_mfma_f32_16x16x32_bf16 v[64:67], v[168:171], v[228:231], v[64:67]
	v_mfma_f32_16x16x32_bf16 v[116:119], v[148:151], v[206:209], v[116:119]
	v_mfma_f32_16x16x32_bf16 v[112:115], v[172:175], v[206:209], v[112:115]
	v_mfma_f32_16x16x32_bf16 v[100:103], v[148:151], v[216:219], v[100:103]
	v_mfma_f32_16x16x32_bf16 v[96:99], v[172:175], v[216:219], v[96:99]
	v_mfma_f32_16x16x32_bf16 v[84:87], v[148:151], v[224:227], v[84:87]
	v_mfma_f32_16x16x32_bf16 v[80:83], v[172:175], v[224:227], v[80:83]
	v_mfma_f32_16x16x32_bf16 v[68:71], v[148:151], v[232:235], v[68:71]
	v_mfma_f32_16x16x32_bf16 v[64:67], v[172:175], v[232:235], v[64:67]
	s_barrier
	s_add_i32 s30, s54, s17
	s_mov_b32 m0, s30
	ds_read_b128 v[202:205], v199 offset:16384
	ds_read_b128 v[206:209], v199 offset:17408
	ds_read_b128 v[210:213], v199 offset:18432
	ds_read_b128 v[216:219], v199 offset:19456
	ds_read_b128 v[220:223], v199 offset:20480
	ds_read_b128 v[224:227], v199 offset:21504
	ds_read_b128 v[228:231], v199 offset:22528
	ds_read_b128 v[232:235], v199 offset:23552
	global_load_lds_dwordx4 v154, s[46:47]
	s_add_i32 m0, s30, 0x2000
	s_add_u32 s30, s46, 0xb0000
	s_addc_u32 s31, s47, 0
	s_add_i32 s34, s55, s17
	global_load_lds_dwordx4 v158, s[46:47]
	s_mov_b32 m0, s34
	s_nop 0
	global_load_lds_dwordx4 v154, s[30:31]
	s_add_i32 m0, s34, 0x2000
	s_nop 0
	global_load_lds_dwordx4 v158, s[30:31]
	s_mov_b32 m0, s18
	s_nop 0
	global_load_lds_dwordx4 v152, s[52:53]
	s_mov_b32 m0, s19
	s_nop 0
	global_load_lds_dwordx4 v156, s[52:53]
	s_waitcnt vmcnt(8)
	s_waitcnt lgkmcnt(0)
	s_barrier
	s_waitcnt lgkmcnt(0)
	v_mfma_f32_16x16x32_bf16 v[60:63], v[128:131], v[202:205], v[60:63]
	v_mfma_f32_16x16x32_bf16 v[56:59], v[136:139], v[202:205], v[56:59]
	v_mfma_f32_16x16x32_bf16 v[44:47], v[128:131], v[210:213], v[44:47]
	v_mfma_f32_16x16x32_bf16 v[40:43], v[136:139], v[210:213], v[40:43]
	v_mfma_f32_16x16x32_bf16 v[28:31], v[128:131], v[220:223], v[28:31]
	v_mfma_f32_16x16x32_bf16 v[24:27], v[136:139], v[220:223], v[24:27]
	v_mfma_f32_16x16x32_bf16 v[12:15], v[128:131], v[228:231], v[12:15]
	v_mfma_f32_16x16x32_bf16 v[8:11], v[136:139], v[228:231], v[8:11]
	v_mfma_f32_16x16x32_bf16 v[60:63], v[132:135], v[206:209], v[60:63]
	v_mfma_f32_16x16x32_bf16 v[56:59], v[140:143], v[206:209], v[56:59]
	v_mfma_f32_16x16x32_bf16 v[44:47], v[132:135], v[216:219], v[44:47]
	v_mfma_f32_16x16x32_bf16 v[40:43], v[140:143], v[216:219], v[40:43]
	v_mfma_f32_16x16x32_bf16 v[28:31], v[132:135], v[224:227], v[28:31]
	v_mfma_f32_16x16x32_bf16 v[24:27], v[140:143], v[224:227], v[24:27]
	v_mfma_f32_16x16x32_bf16 v[12:15], v[132:135], v[232:235], v[12:15]
	v_mfma_f32_16x16x32_bf16 v[8:11], v[140:143], v[232:235], v[8:11]
	v_mfma_f32_16x16x32_bf16 v[52:55], v[144:147], v[202:205], v[52:55]
	v_mfma_f32_16x16x32_bf16 v[48:51], v[168:171], v[202:205], v[48:51]
	v_mfma_f32_16x16x32_bf16 v[36:39], v[144:147], v[210:213], v[36:39]
	v_mfma_f32_16x16x32_bf16 v[32:35], v[168:171], v[210:213], v[32:35]
	v_mfma_f32_16x16x32_bf16 v[20:23], v[144:147], v[220:223], v[20:23]
	v_mfma_f32_16x16x32_bf16 v[16:19], v[168:171], v[220:223], v[16:19]
	v_mfma_f32_16x16x32_bf16 v[4:7], v[144:147], v[228:231], v[4:7]
	v_mfma_f32_16x16x32_bf16 v[0:3], v[168:171], v[228:231], v[0:3]
	v_mfma_f32_16x16x32_bf16 v[52:55], v[148:151], v[206:209], v[52:55]
	v_mfma_f32_16x16x32_bf16 v[48:51], v[172:175], v[206:209], v[48:51]
	v_mfma_f32_16x16x32_bf16 v[36:39], v[148:151], v[216:219], v[36:39]
	v_mfma_f32_16x16x32_bf16 v[32:35], v[172:175], v[216:219], v[32:35]
	v_mfma_f32_16x16x32_bf16 v[20:23], v[148:151], v[224:227], v[20:23]
	v_mfma_f32_16x16x32_bf16 v[16:19], v[172:175], v[224:227], v[16:19]
	v_mfma_f32_16x16x32_bf16 v[4:7], v[148:151], v[232:235], v[4:7]
	v_mfma_f32_16x16x32_bf16 v[0:3], v[172:175], v[232:235], v[0:3]
	s_barrier
	s_add_i32 s34, 0, 0x18000
	s_add_i32 s35, 0, 0x1c000
	ds_read_b128 v[128:131], v197 offset:32768
	ds_read_b128 v[132:135], v197 offset:33792
	ds_read_b128 v[136:139], v197 offset:34816
	ds_read_b128 v[140:143], v197 offset:35840
	ds_read_b128 v[144:147], v197 offset:49152
	ds_read_b128 v[148:151], v197 offset:50176
	ds_read_b128 v[168:171], v197 offset:51200
	ds_read_b128 v[172:175], v197 offset:52224
	s_add_u32 s30, s52, 0xb0000
	s_addc_u32 s31, s53, 0
	s_mov_b32 m0, s20
	ds_read_b128 v[202:205], v199 offset:32768
	ds_read_b128 v[206:209], v199 offset:33792
	ds_read_b128 v[210:213], v199 offset:34816
	ds_read_b128 v[216:219], v199 offset:35840
	ds_read_b128 v[220:223], v199 offset:36864
	ds_read_b128 v[224:227], v199 offset:37888
	ds_read_b128 v[228:231], v199 offset:38912
	ds_read_b128 v[232:235], v199 offset:39936
	global_load_lds_dwordx4 v152, s[30:31]
	s_mov_b32 m0, s21
	s_nop 0
	global_load_lds_dwordx4 v156, s[30:31]
	s_waitcnt vmcnt(8)
	s_waitcnt lgkmcnt(0)
	s_barrier
	s_waitcnt lgkmcnt(0)
	v_mfma_f32_16x16x32_bf16 v[124:127], v[128:131], v[202:205], v[124:127]
	v_mfma_f32_16x16x32_bf16 v[120:123], v[136:139], v[202:205], v[120:123]
	v_mfma_f32_16x16x32_bf16 v[108:111], v[128:131], v[210:213], v[108:111]
	v_mfma_f32_16x16x32_bf16 v[104:107], v[136:139], v[210:213], v[104:107]
	v_mfma_f32_16x16x32_bf16 v[92:95], v[128:131], v[220:223], v[92:95]
	v_mfma_f32_16x16x32_bf16 v[88:91], v[136:139], v[220:223], v[88:91]
	v_mfma_f32_16x16x32_bf16 v[76:79], v[128:131], v[228:231], v[76:79]
	v_mfma_f32_16x16x32_bf16 v[72:75], v[136:139], v[228:231], v[72:75]
	v_mfma_f32_16x16x32_bf16 v[124:127], v[132:135], v[206:209], v[124:127]
	v_mfma_f32_16x16x32_bf16 v[120:123], v[140:143], v[206:209], v[120:123]
	v_mfma_f32_16x16x32_bf16 v[108:111], v[132:135], v[216:219], v[108:111]
	v_mfma_f32_16x16x32_bf16 v[104:107], v[140:143], v[216:219], v[104:107]
	v_mfma_f32_16x16x32_bf16 v[92:95], v[132:135], v[224:227], v[92:95]
	v_mfma_f32_16x16x32_bf16 v[88:91], v[140:143], v[224:227], v[88:91]
	v_mfma_f32_16x16x32_bf16 v[76:79], v[132:135], v[232:235], v[76:79]
	v_mfma_f32_16x16x32_bf16 v[72:75], v[140:143], v[232:235], v[72:75]
	v_mfma_f32_16x16x32_bf16 v[116:119], v[144:147], v[202:205], v[116:119]
	v_mfma_f32_16x16x32_bf16 v[112:115], v[168:171], v[202:205], v[112:115]
	v_mfma_f32_16x16x32_bf16 v[100:103], v[144:147], v[210:213], v[100:103]
	v_mfma_f32_16x16x32_bf16 v[96:99], v[168:171], v[210:213], v[96:99]
	v_mfma_f32_16x16x32_bf16 v[84:87], v[144:147], v[220:223], v[84:87]
	v_mfma_f32_16x16x32_bf16 v[80:83], v[168:171], v[220:223], v[80:83]
	v_mfma_f32_16x16x32_bf16 v[68:71], v[144:147], v[228:231], v[68:71]
	v_mfma_f32_16x16x32_bf16 v[64:67], v[168:171], v[228:231], v[64:67]
	v_mfma_f32_16x16x32_bf16 v[116:119], v[148:151], v[206:209], v[116:119]
	v_mfma_f32_16x16x32_bf16 v[112:115], v[172:175], v[206:209], v[112:115]
	v_mfma_f32_16x16x32_bf16 v[100:103], v[148:151], v[216:219], v[100:103]
	v_mfma_f32_16x16x32_bf16 v[96:99], v[172:175], v[216:219], v[96:99]
	v_mfma_f32_16x16x32_bf16 v[84:87], v[148:151], v[224:227], v[84:87]
	v_mfma_f32_16x16x32_bf16 v[80:83], v[172:175], v[224:227], v[80:83]
	v_mfma_f32_16x16x32_bf16 v[68:71], v[148:151], v[232:235], v[68:71]
	v_mfma_f32_16x16x32_bf16 v[64:67], v[172:175], v[232:235], v[64:67]
	s_barrier
	s_add_i32 m0, s34, s17
	s_add_u32 s30, s46, 0x80
	s_addc_u32 s31, s47, 0
	ds_read_b128 v[202:205], v199 offset:49152
	ds_read_b128 v[206:209], v199 offset:50176
	ds_read_b128 v[210:213], v199 offset:51200
	ds_read_b128 v[216:219], v199 offset:52224
	ds_read_b128 v[220:223], v199 offset:53248
	ds_read_b128 v[224:227], v199 offset:54272
	ds_read_b128 v[228:231], v199 offset:55296
	ds_read_b128 v[232:235], v199 offset:56320
	global_load_lds_dwordx4 v154, s[30:31]
	s_add_i32 m0, m0, 0x2000
	s_add_i32 s34, s35, s17
	global_load_lds_dwordx4 v158, s[30:31]
	s_add_u32 s30, s30, 0xb0000
	s_addc_u32 s31, s31, 0
	s_mov_b32 m0, s34
	s_nop 0
	global_load_lds_dwordx4 v154, s[30:31]
	s_add_i32 m0, s34, 0x2000
	s_nop 0
	global_load_lds_dwordx4 v158, s[30:31]
	s_add_u32 s30, s52, 0x80
	s_addc_u32 s31, s53, 0
	s_mov_b32 m0, s25
	s_nop 0
	global_load_lds_dwordx4 v152, s[30:31]
	s_mov_b32 m0, s26
	s_nop 0
	global_load_lds_dwordx4 v156, s[30:31]
	s_add_u32 s30, s46, 0xb0080
	s_addc_u32 s31, s47, 0
	s_waitcnt vmcnt(8)
	s_waitcnt lgkmcnt(0)
	s_barrier
	s_waitcnt lgkmcnt(0)
	v_mfma_f32_16x16x32_bf16 v[60:63], v[128:131], v[202:205], v[60:63]
	v_mfma_f32_16x16x32_bf16 v[56:59], v[136:139], v[202:205], v[56:59]
	v_mfma_f32_16x16x32_bf16 v[44:47], v[128:131], v[210:213], v[44:47]
	v_mfma_f32_16x16x32_bf16 v[40:43], v[136:139], v[210:213], v[40:43]
	v_mfma_f32_16x16x32_bf16 v[28:31], v[128:131], v[220:223], v[28:31]
	v_mfma_f32_16x16x32_bf16 v[24:27], v[136:139], v[220:223], v[24:27]
	v_mfma_f32_16x16x32_bf16 v[12:15], v[128:131], v[228:231], v[12:15]
	v_mfma_f32_16x16x32_bf16 v[8:11], v[136:139], v[228:231], v[8:11]
	v_mfma_f32_16x16x32_bf16 v[60:63], v[132:135], v[206:209], v[60:63]
	v_mfma_f32_16x16x32_bf16 v[56:59], v[140:143], v[206:209], v[56:59]
	v_mfma_f32_16x16x32_bf16 v[44:47], v[132:135], v[216:219], v[44:47]
	v_mfma_f32_16x16x32_bf16 v[40:43], v[140:143], v[216:219], v[40:43]
	v_mfma_f32_16x16x32_bf16 v[28:31], v[132:135], v[224:227], v[28:31]
	v_mfma_f32_16x16x32_bf16 v[24:27], v[140:143], v[224:227], v[24:27]
	v_mfma_f32_16x16x32_bf16 v[12:15], v[132:135], v[232:235], v[12:15]
	v_mfma_f32_16x16x32_bf16 v[8:11], v[140:143], v[232:235], v[8:11]
	v_mfma_f32_16x16x32_bf16 v[52:55], v[144:147], v[202:205], v[52:55]
	v_mfma_f32_16x16x32_bf16 v[48:51], v[168:171], v[202:205], v[48:51]
	v_mfma_f32_16x16x32_bf16 v[36:39], v[144:147], v[210:213], v[36:39]
	v_mfma_f32_16x16x32_bf16 v[32:35], v[168:171], v[210:213], v[32:35]
	v_mfma_f32_16x16x32_bf16 v[20:23], v[144:147], v[220:223], v[20:23]
	v_mfma_f32_16x16x32_bf16 v[16:19], v[168:171], v[220:223], v[16:19]
	v_mfma_f32_16x16x32_bf16 v[4:7], v[144:147], v[228:231], v[4:7]
	v_mfma_f32_16x16x32_bf16 v[0:3], v[168:171], v[228:231], v[0:3]
	v_mfma_f32_16x16x32_bf16 v[52:55], v[148:151], v[206:209], v[52:55]
	v_mfma_f32_16x16x32_bf16 v[48:51], v[172:175], v[206:209], v[48:51]
	v_mfma_f32_16x16x32_bf16 v[36:39], v[148:151], v[216:219], v[36:39]
	v_mfma_f32_16x16x32_bf16 v[32:35], v[172:175], v[216:219], v[32:35]
	v_mfma_f32_16x16x32_bf16 v[20:23], v[148:151], v[224:227], v[20:23]
	v_mfma_f32_16x16x32_bf16 v[16:19], v[172:175], v[224:227], v[16:19]
	v_mfma_f32_16x16x32_bf16 v[4:7], v[148:151], v[232:235], v[4:7]
	v_mfma_f32_16x16x32_bf16 v[0:3], v[172:175], v[232:235], v[0:3]
	s_barrier
	s_add_i32 s15, s15, 2
	s_add_u32 s13, s13, 0x100
	s_addc_u32 s14, s14, 0
	s_cmp_gt_u32 s15, 41
	s_mov_b64 s[44:45], s[42:43]
	s_cbranch_scc0 .LBB0_955
	s_setprio 0
	s_and_b64 vcc, exec, s[6:7]
	s_cbranch_vccz .LBB0_958
	s_barrier
